# first grid barrier: the 16 per-XCD arrival counters loaded back to back with one wait (were 16 serialized round trips), padded to keep later code placement
# baseline (speedup 1.0000x reference)
.LBB0_134:
	v_readlane_b32 s2, v253, 11
	v_readlane_b32 s3, v253, 12
	s_waitcnt lgkmcnt(0)
	s_mov_b64 s[40:41], -1
	s_mov_b64 s[42:43], -1
	global_load_dword v0, v177, s[90:91] sc1
	global_load_dword v1, v177, s[90:91] offset:256 sc1
	global_load_dword v2, v177, s[90:91] offset:512 sc1
	global_load_dword v3, v177, s[90:91] offset:768 sc1
	global_load_dword v4, v177, s[90:91] offset:1024 sc1
	global_load_dword v5, v177, s[90:91] offset:1280 sc1
	global_load_dword v6, v177, s[90:91] offset:1536 sc1
	global_load_dword v7, v177, s[90:91] offset:1792 sc1
	global_load_dword v8, v177, s[90:91] offset:2048 sc1
	global_load_dword v9, v177, s[90:91] offset:2304 sc1
	global_load_dword v10, v177, s[90:91] offset:2560 sc1
	global_load_dword v11, v177, s[90:91] offset:2816 sc1
	global_load_dword v12, v177, s[90:91] offset:3072 sc1
	global_load_dword v13, v177, s[90:91] offset:3328 sc1
	global_load_dword v14, v177, s[90:91] offset:3584 sc1
	global_load_dword v15, v177, s[90:91] offset:3840 sc1
	v_readlane_b32 s2, v255, 3
	s_waitcnt vmcnt(0)
	v_add_u32_e32 v16, v1, v0
	v_add_u32_e32 v16, v16, v2
	v_add_u32_e32 v16, v16, v3
	v_add_u32_e32 v16, v16, v4
	v_add_u32_e32 v16, v16, v5
	v_add_u32_e32 v16, v16, v6
	v_add_u32_e32 v16, v16, v7
	v_add_u32_e32 v16, v16, v8
	v_add_u32_e32 v16, v16, v9
	v_add_u32_e32 v16, v16, v10
	v_add_u32_e32 v16, v16, v11
	v_add_u32_e32 v16, v16, v12
	v_add_u32_e32 v16, v16, v13
	v_add_u32_e32 v16, v16, v14
	v_add_u32_e32 v16, v16, v15
	s_nop 0
	s_nop 0
	s_nop 0
	s_nop 0
	s_nop 0
	v_cmp_eq_u32_e32 vcc, s2, v16
	s_cbranch_vccnz .LBB0_133
	s_and_b32 s2, s1, 0xff
	s_cmp_eq_u32 s2, 0
	s_mov_b64 s[44:45], -1
	s_sleep 1
	s_cbranch_scc0 .LBB0_138
	v_readlane_b32 s2, v253, 9
	v_readlane_b32 s3, v253, 10
	s_nop 4
	global_load_dword v16, v177, s[2:3] sc1
	s_waitcnt vmcnt(0)
	v_cmp_eq_u32_e32 vcc, 0, v16
	s_cbranch_vccnz .LBB0_140
	s_mov_b64 s[44:45], 0
